# nt policy on the RG-LRU row loads (read once), on top of previous
# baseline (speedup 1.0000x reference)
; __device__ __forceinline__ void unit(LAS unsigned char* lds, const Args& a, int l, int tk, int wave, int lane, int tid) {
;     ...
;     if (tid < 320) { const int j = tid >> 6, ch = tid & 63; CWL[tid] = j < 4 ? a.in[I_CONVW][((size_t)l * 4 + j) * LW + 64 * blk + ch] : a.in[I_CONVB][l * LW + 64 * blk + ch]; }
;     __syncthreads();
;     v4u px[5], pg[2];
;     ...
;     LRU_FETCH(0);
.LBB0_550:
	s_or_b64 exec, exec, s[8:9]
	v_lshlrev_b32_e32 v0, 3, v125
	v_and_b32_e32 v75, 56, v0
	v_or_b32_e32 v2, s3, v75
	v_ashrrev_i32_e32 v74, 3, v4
	s_lshl_b32 s3, s62, 9
	v_lshlrev_b32_e32 v73, 1, v74
	s_and_b32 s22, s3, 0xfffff800
	v_add_u32_e32 v3, s22, v73
	v_mov_b64_e32 v[0:1], s[76:77]
	v_mad_i64_i32 v[0:1], s[8:9], v3, s75, v[0:1]
	v_lshlrev_b32_e32 v68, 1, v2
	v_mov_b32_e32 v69, v16
	v_lshl_add_u64 v[0:1], v[0:1], 0, v[68:69]
	v_lshl_add_u64 v[70:71], v[0:1], 0, s[36:37]
	v_mov_b32_e32 v0, 0
	v_cmp_lt_i32_e32 vcc, 1, v74
	v_mov_b32_e32 v1, v0
	v_mov_b32_e32 v2, v0
	v_mov_b32_e32 v3, v0
	s_waitcnt lgkmcnt(0)
	s_barrier
	s_and_saveexec_b64 s[8:9], vcc
	s_cbranch_execz .LBB0_552
	v_add_co_u32_e32 v0, vcc, 0xffffc000, v70
	s_nop 1
	v_addc_co_u32_e32 v1, vcc, -1, v71, vcc
	global_load_dwordx4 v[0:3], v[0:1], off offset:-512 nt
.LBB0_552:
	s_or_b64 exec, exec, s[8:9]
	v_mov_b32_e32 v4, v16
	v_mov_b32_e32 v5, v16
	v_mov_b32_e32 v6, v16
	v_mov_b32_e32 v7, v16
	s_waitcnt vmcnt(0)
	v_mov_b32_e32 v34, v0
	v_mov_b32_e32 v35, v1
	v_mov_b32_e32 v36, v2
	v_mov_b32_e32 v37, v3
	v_mov_b32_e32 v38, v16
	v_mov_b32_e32 v39, v16
	v_mov_b32_e32 v40, v16
	v_mov_b32_e32 v41, v16
	v_mov_b32_e32 v42, v16
	v_mov_b32_e32 v43, v16
	v_mov_b32_e32 v44, v16
	v_mov_b32_e32 v45, v16
	v_mov_b32_e32 v18, v0
	v_mov_b32_e32 v19, v1
	v_mov_b32_e32 v20, v2
	v_mov_b32_e32 v21, v3
	v_mov_b32_e32 v22, v16
	v_mov_b32_e32 v23, v16
	v_mov_b32_e32 v24, v16
	v_mov_b32_e32 v25, v16
	v_mov_b32_e32 v26, v16
	v_mov_b32_e32 v27, v16
	v_mov_b32_e32 v28, v16
	v_mov_b32_e32 v29, v16
	v_mov_b32_e32 v30, v16
	v_mov_b32_e32 v31, v16
	v_mov_b32_e32 v32, v16
	v_mov_b32_e32 v33, v16
	v_cmp_lt_i32_e64 s[42:43], 0, v74
	s_and_saveexec_b64 s[8:9], s[42:43]
	s_cbranch_execz .LBB0_580
	v_add_co_u32_e32 v4, vcc, 0xffffe000, v70
	v_mov_b32_e32 v30, v16
	s_nop 0
	v_addc_co_u32_e32 v5, vcc, -1, v71, vcc
	global_load_dwordx4 v[4:7], v[4:5], off offset:-3072 nt
	v_mov_b32_e32 v31, v16
	v_mov_b32_e32 v8, v16
	v_mov_b32_e32 v9, v16
	v_mov_b32_e32 v10, v16
	v_mov_b32_e32 v11, v16
	v_mov_b32_e32 v18, v0
	v_mov_b32_e32 v19, v1
	v_mov_b32_e32 v20, v2
	v_mov_b32_e32 v21, v3
	v_mov_b32_e32 v26, v16
	v_mov_b32_e32 v27, v16
	v_mov_b32_e32 v28, v16
	v_mov_b32_e32 v29, v16
	v_mov_b32_e32 v32, v16
	v_mov_b32_e32 v33, v16
	s_waitcnt vmcnt(0)
	v_mov_b32_e32 v22, v4
	v_mov_b32_e32 v23, v5
	v_mov_b32_e32 v24, v6
	v_mov_b32_e32 v25, v7
	v_mov_b64_e32 v[64:65], v[30:31]
	v_mov_b64_e32 v[44:45], v[10:11]
	v_mov_b64_e32 v[42:43], v[8:9]
	v_mov_b64_e32 v[40:41], v[6:7]
	v_mov_b64_e32 v[38:39], v[4:5]
	v_mov_b64_e32 v[36:37], v[2:3]
	v_mov_b64_e32 v[34:35], v[0:1]
	v_mov_b64_e32 v[62:63], v[28:29]
	v_mov_b64_e32 v[60:61], v[26:27]
	v_mov_b64_e32 v[58:59], v[24:25]
	v_mov_b64_e32 v[56:57], v[22:23]
	v_mov_b64_e32 v[54:55], v[20:21]
	v_mov_b64_e32 v[52:53], v[18:19]
	v_mov_b64_e32 v[50:51], v[16:17]
	v_mov_b64_e32 v[48:49], v[14:15]
	v_mov_b64_e32 v[46:47], v[12:13]
	s_or_b64 exec, exec, s[8:9]
	s_and_saveexec_b64 s[8:9], s[42:43]
	s_cbranch_execnz .LBB0_581

; #define LAS __attribute__((address_space(3)))
; __device__ __forceinline__ void unit(LAS unsigned char* lds, const Args& a, int l, int tk, int wave, int lane, int tid) {
;     ...
;     float ba[4], bx[4], csp[4], carry[4];
; #pragma unroll
;     for (int nt = 0; nt < 4; ++nt) { const int ch = l * LW + 64 * blk + 16 * nt + fr; ba[nt] = a.in[I_BA][ch]; bx[nt] = a.in[I_BX][ch]; csp[nt] = 8.0f * log1pf(expf(-a.in[I_LAM][ch])); carry[nt] = 0.f; }
;     const int c8 = tid & 7, chb = 64 * blk + 8 * c8;
;     LAS unsigned char* XC = lds + XC_OFF; LAS float* XCF = (LAS float*)(lds + XCF_OFF); LAS bf16* XG = (LAS bf16*)(lds + XG_OFF); LAS bf16* OUT = (LAS bf16*)(lds + OUT_OFF); LAS float* AGG = (LAS float*)(lds + AGG_OFF);
;     LAS float* CWL = (LAS float*)(lds + CWL_OFF);
;     if (tid < 320) { const int j = tid >> 6, ch = tid & 63; CWL[tid] = j < 4 ? a.in[I_CONVW][((size_t)l * 4 + j) * LW + 64 * blk + ch] : a.in[I_CONVB][l * LW + 64 * blk + ch]; }
;     __syncthreads();
;     v4u px[5], pg[2];
;     ...
;     LRU_FETCH(0);
.LBB0_555:
	global_load_dwordx4 v[46:49], v[70:71], off nt
	s_waitcnt vmcnt(0)
	v_mov_b64_e32 v[18:19], v[34:35]
	v_mov_b64_e32 v[20:21], v[36:37]
	v_mov_b64_e32 v[22:23], v[38:39]
	v_mov_b64_e32 v[24:25], v[40:41]
	v_mov_b64_e32 v[26:27], v[42:43]
	v_mov_b64_e32 v[28:29], v[44:45]
	v_mov_b64_e32 v[30:31], v[46:47]
	v_mov_b64_e32 v[32:33], v[48:49]
	v_mov_b64_e32 v[34:35], v[50:51]
	v_mov_b64_e32 v[36:37], v[52:53]
	v_mov_b64_e32 v[38:39], v[54:55]
	v_mov_b64_e32 v[40:41], v[56:57]
	v_mov_b64_e32 v[42:43], v[58:59]
	v_mov_b64_e32 v[44:45], v[60:61]
	v_mov_b64_e32 v[46:47], v[62:63]
	v_mov_b64_e32 v[48:49], v[64:65]
.LBB0_556:
	s_or_b64 exec, exec, s[8:9]
	v_mov_b32_e32 v34, v16
	v_mov_b32_e32 v35, v16
	v_mov_b32_e32 v36, v16
	v_mov_b32_e32 v37, v16
	s_and_saveexec_b64 s[8:9], vcc
	s_cbranch_execz .LBB0_558
	v_add_co_u32_e32 v0, vcc, 0x1000, v70
	s_nop 1
	v_addc_co_u32_e32 v1, vcc, 0, v71, vcc
	global_load_dwordx4 v[34:37], v[0:1], off offset:1536 nt
.LBB0_558:
	s_or_b64 exec, exec, s[8:9]
	v_mul_f32_e32 v0, 0xbfb8aa3b, v79
	v_rndne_f32_e32 v1, v0
	s_mov_b32 s8, 0xbfb8aa3b
	v_sub_f32_e32 v2, v0, v1
	v_fma_f32 v0, v79, s8, -v0
	v_fmac_f32_e32 v0, 0xb2a5705f, v79
	v_add_f32_e32 v0, v2, v0
	v_cvt_i32_f32_e32 v1, v1
	v_exp_f32_e32 v0, v0
	s_mov_b32 s9, 0x42ce8ed0
	v_cmp_nlt_f32_e32 vcc, s9, v79
	s_mov_b32 s21, 0xc2b17218
	v_ldexp_f32 v0, v0, v1
	v_cndmask_b32_e32 v0, 0, v0, vcc
	v_cmp_ngt_f32_e32 vcc, s21, v79
	s_mov_b32 s25, 0x3f2aaaab
	s_mov_b32 s34, 0x3f317218
	v_cndmask_b32_e32 v2, v236, v0, vcc
	v_add_f32_e32 v3, 1.0, v2
	v_add_f32_e32 v0, -1.0, v3
	v_sub_f32_e32 v1, v0, v3
	v_add_f32_e32 v1, 1.0, v1
	v_sub_f32_e32 v0, v2, v0
	v_add_f32_e32 v4, v0, v1
	v_frexp_mant_f32_e32 v5, v3
	v_cvt_f64_f32_e32 v[0:1], v3
	v_frexp_exp_i32_f64_e32 v0, v[0:1]
	v_cmp_gt_f32_e32 vcc, s25, v5
	s_mov_b32 s23, 0x7f800000
	s_mov_b32 s35, 0x33800000
	v_subbrev_co_u32_e32 v0, vcc, 0, v0, vcc
	v_sub_u32_e32 v1, 0, v0
	v_ldexp_f32 v3, v3, v1
	v_ldexp_f32 v1, v4, v1
	v_add_f32_e32 v4, -1.0, v3
	v_add_f32_e32 v7, 1.0, v3
	v_add_f32_e32 v5, 1.0, v4
	v_add_f32_e32 v8, -1.0, v7
	v_sub_f32_e32 v5, v3, v5
	v_sub_f32_e32 v3, v3, v8
	v_add_f32_e32 v5, v1, v5
	v_add_f32_e32 v1, v1, v3
	v_add_f32_e32 v3, v7, v1
	v_rcp_f32_e32 v8, v3
	v_add_f32_e32 v6, v4, v5
	v_sub_f32_e32 v4, v4, v6
	v_add_f32_e32 v4, v5, v4
	v_sub_f32_e32 v5, v7, v3
	v_add_f32_e32 v1, v1, v5
	v_mul_f32_e32 v5, v6, v8
	v_mul_f32_e32 v7, v3, v5
	v_fma_f32 v9, v5, v3, -v7
	v_fmac_f32_e32 v9, v5, v1
	v_add_f32_e32 v10, v7, v9
	v_sub_f32_e32 v11, v6, v10
	v_sub_f32_e32 v6, v6, v11
	v_sub_f32_e32 v7, v10, v7
	v_sub_f32_e32 v6, v6, v10
	v_add_f32_e32 v4, v4, v6
	v_sub_f32_e32 v6, v7, v9
	v_add_f32_e32 v4, v6, v4
	v_add_f32_e32 v6, v11, v4
	v_mul_f32_e32 v7, v8, v6
	v_mul_f32_e32 v9, v3, v7
	v_fma_f32 v3, v7, v3, -v9
	v_fmac_f32_e32 v3, v7, v1
	v_sub_f32_e32 v1, v11, v6
	v_add_f32_e32 v1, v4, v1
	v_add_f32_e32 v4, v9, v3
	v_sub_f32_e32 v10, v6, v4
	v_sub_f32_e32 v6, v6, v10
	v_sub_f32_e32 v9, v4, v9
	v_sub_f32_e32 v4, v6, v4
	v_add_f32_e32 v1, v1, v4
	v_sub_f32_e32 v3, v9, v3
	v_cvt_f32_i32_e32 v0, v0
	v_add_f32_e32 v1, v3, v1
	v_add_f32_e32 v3, v5, v7
	v_add_f32_e32 v1, v10, v1
	v_sub_f32_e32 v4, v3, v5
	v_mul_f32_e32 v1, v8, v1
	v_sub_f32_e32 v4, v7, v4
	v_add_f32_e32 v1, v4, v1
	v_mul_f32_e32 v7, 0x3f317218, v0
	v_add_f32_e32 v4, v3, v1
	v_fma_f32 v8, v0, s34, -v7
	v_mul_f32_e32 v5, v4, v4
	v_fmac_f32_e32 v8, 0xb102e308, v0
	v_sub_f32_e32 v0, v4, v3
	v_fmamk_f32 v6, v5, 0x3e9b6dac, v228
	v_sub_f32_e32 v0, v1, v0
	v_add_f32_e32 v1, v7, v8
	v_fmaak_f32 v6, v5, v6, 0x3f2aaada
	v_sub_f32_e32 v3, v1, v7
	v_ldexp_f32 v7, v4, 1
	v_mul_f32_e32 v4, v4, v5
	v_mul_f32_e32 v4, v4, v6
	v_add_f32_e32 v5, v7, v4
	v_sub_f32_e32 v6, v5, v7
	v_ldexp_f32 v0, v0, 1
	v_sub_f32_e32 v4, v4, v6
	v_add_f32_e32 v0, v0, v4
	v_add_f32_e32 v4, v5, v0
	v_sub_f32_e32 v5, v4, v5
	v_sub_f32_e32 v0, v0, v5
	v_add_f32_e32 v5, v1, v4
	v_sub_f32_e32 v6, v5, v1
	v_sub_f32_e32 v7, v5, v6
	v_sub_f32_e32 v3, v8, v3
	v_sub_f32_e32 v1, v1, v7
	v_sub_f32_e32 v4, v4, v6
	v_add_f32_e32 v1, v4, v1
	v_add_f32_e32 v4, v3, v0
	v_sub_f32_e32 v6, v4, v3
	v_sub_f32_e32 v7, v4, v6
	v_sub_f32_e32 v3, v3, v7
	v_sub_f32_e32 v0, v0, v6
	v_add_f32_e32 v1, v4, v1
	v_add_f32_e32 v0, v0, v3
	v_add_f32_e32 v3, v5, v1
	v_sub_f32_e32 v4, v3, v5
	v_sub_f32_e32 v1, v1, v4
	v_add_f32_e32 v0, v0, v1
	v_mul_f32_e32 v1, 0xbfb8aa3b, v78
	v_add_f32_e32 v0, v3, v0
	v_rndne_f32_e32 v3, v1
	v_sub_f32_e32 v4, v1, v3
	v_fma_f32 v1, v78, s8, -v1
	v_fmac_f32_e32 v1, 0xb2a5705f, v78
	v_add_f32_e32 v1, v4, v1
	v_exp_f32_e32 v1, v1
	v_cvt_i32_f32_e32 v3, v3
	v_cmp_neq_f32_e32 vcc, s23, v2
	v_add_u32_e32 v42, -16, v237
	v_and_b32_e32 v43, 64, v237
	v_cndmask_b32_e32 v0, v236, v0, vcc
	v_cmp_lt_f32_e64 vcc, |v2|, s35
	v_lshrrev_b32_e32 v39, 1, v125
	v_add_u32_e32 v41, 4, v72
	v_cndmask_b32_e32 v8, v0, v2, vcc
	v_ldexp_f32 v0, v1, v3
	v_cmp_nlt_f32_e32 vcc, s9, v78
	v_or_b32_e32 v38, s4, v17
	v_bitop3_b32 v40, v39, v72, 7 bitop3:0x6c
	v_cndmask_b32_e32 v0, 0, v0, vcc
	v_cmp_ngt_f32_e32 vcc, s21, v78
	v_bitop3_b32 v39, v41, v39, 7 bitop3:0x78
	v_lshl_add_u32 v41, v72, 2, s4
	v_cndmask_b32_e32 v2, v236, v0, vcc
	v_add_f32_e32 v3, 1.0, v2
	v_add_f32_e32 v0, -1.0, v3
	v_sub_f32_e32 v1, v0, v3
	v_add_f32_e32 v1, 1.0, v1
	v_sub_f32_e32 v0, v2, v0
	v_add_f32_e32 v4, v0, v1
	v_frexp_mant_f32_e32 v5, v3
	v_cvt_f64_f32_e32 v[0:1], v3
	v_frexp_exp_i32_f64_e32 v0, v[0:1]
	v_cmp_gt_f32_e32 vcc, s25, v5
	s_lshl_b32 s4, s2, 9
	v_lshlrev_b32_e32 v47, 4, v125
	v_subbrev_co_u32_e32 v0, vcc, 0, v0, vcc
	v_sub_u32_e32 v1, 0, v0
	v_ldexp_f32 v3, v3, v1
	v_ldexp_f32 v1, v4, v1
	v_add_f32_e32 v4, -1.0, v3
; #define LAS __attribute__((address_space(3)))
; __device__ __forceinline__ void unit(LAS unsigned char* lds, const Args& a, int l, int tk, int wave, int lane, int tid) {
;     ...
;     float ba[4], bx[4], csp[4], carry[4];
; #pragma unroll
;     for (int nt = 0; nt < 4; ++nt) { const int ch = l * LW + 64 * blk + 16 * nt + fr; ba[nt] = a.in[I_BA][ch]; bx[nt] = a.in[I_BX][ch]; csp[nt] = 8.0f * log1pf(expf(-a.in[I_LAM][ch])); carry[nt] = 0.f; }
;     const int c8 = tid & 7, chb = 64 * blk + 8 * c8;
;     LAS unsigned char* XC = lds + XC_OFF; LAS float* XCF = (LAS float*)(lds + XCF_OFF); LAS bf16* XG = (LAS bf16*)(lds + XG_OFF); LAS bf16* OUT = (LAS bf16*)(lds + OUT_OFF); LAS float* AGG = (LAS float*)(lds + AGG_OFF);
	v_add_f32_e32 v7, 1.0, v3
	v_add_f32_e32 v5, 1.0, v4
	v_add_f32_e32 v9, -1.0, v7
	v_sub_f32_e32 v5, v3, v5
	v_sub_f32_e32 v3, v3, v9
	v_add_f32_e32 v5, v1, v5
	v_add_f32_e32 v1, v1, v3
	v_add_f32_e32 v3, v7, v1
	v_rcp_f32_e32 v9, v3
	v_add_f32_e32 v6, v4, v5
	v_sub_f32_e32 v4, v4, v6
	v_add_f32_e32 v4, v5, v4
	v_sub_f32_e32 v5, v7, v3
	v_add_f32_e32 v1, v1, v5
	v_mul_f32_e32 v5, v6, v9
	v_mul_f32_e32 v7, v3, v5
	v_fma_f32 v10, v5, v3, -v7
	v_fmac_f32_e32 v10, v5, v1
	v_add_f32_e32 v11, v7, v10
	v_sub_f32_e32 v12, v6, v11
	v_sub_f32_e32 v6, v6, v12
	v_sub_f32_e32 v7, v11, v7
	v_sub_f32_e32 v6, v6, v11
	v_add_f32_e32 v4, v4, v6
	v_sub_f32_e32 v6, v7, v10
	v_add_f32_e32 v4, v6, v4
	v_add_f32_e32 v6, v12, v4
	v_mul_f32_e32 v7, v9, v6
	v_mul_f32_e32 v10, v3, v7
	v_fma_f32 v3, v7, v3, -v10
	v_fmac_f32_e32 v3, v7, v1
	v_sub_f32_e32 v1, v12, v6
	v_add_f32_e32 v1, v4, v1
	v_add_f32_e32 v4, v10, v3
	v_sub_f32_e32 v11, v6, v4
	v_sub_f32_e32 v6, v6, v11
	v_sub_f32_e32 v10, v4, v10
	v_sub_f32_e32 v4, v6, v4
	v_add_f32_e32 v1, v1, v4
	v_sub_f32_e32 v3, v10, v3
	v_cvt_f32_i32_e32 v0, v0
	v_add_f32_e32 v1, v3, v1
	v_add_f32_e32 v3, v5, v7
	v_add_f32_e32 v1, v11, v1
	v_sub_f32_e32 v4, v3, v5
	v_mul_f32_e32 v1, v9, v1
	v_sub_f32_e32 v4, v7, v4
	v_add_f32_e32 v1, v4, v1
	v_mul_f32_e32 v7, 0x3f317218, v0
	v_add_f32_e32 v4, v3, v1
	v_fma_f32 v9, v0, s34, -v7
	v_mul_f32_e32 v5, v4, v4
	v_fmac_f32_e32 v9, 0xb102e308, v0
	v_sub_f32_e32 v0, v4, v3
	v_fmamk_f32 v6, v5, 0x3e9b6dac, v228
	v_sub_f32_e32 v0, v1, v0
	v_add_f32_e32 v1, v7, v9
	v_fmaak_f32 v6, v5, v6, 0x3f2aaada
	v_sub_f32_e32 v3, v1, v7
	v_ldexp_f32 v7, v4, 1
	v_mul_f32_e32 v4, v4, v5
	v_mul_f32_e32 v4, v4, v6
	v_add_f32_e32 v5, v7, v4
	v_sub_f32_e32 v6, v5, v7
	v_ldexp_f32 v0, v0, 1
	v_sub_f32_e32 v4, v4, v6
	v_add_f32_e32 v0, v0, v4
	v_add_f32_e32 v4, v5, v0
	v_sub_f32_e32 v5, v4, v5
	v_sub_f32_e32 v0, v0, v5
	v_add_f32_e32 v5, v1, v4
	v_sub_f32_e32 v6, v5, v1
	v_sub_f32_e32 v7, v5, v6
	v_sub_f32_e32 v3, v9, v3
	v_sub_f32_e32 v1, v1, v7
	v_sub_f32_e32 v4, v4, v6
	v_add_f32_e32 v1, v4, v1
	v_add_f32_e32 v4, v3, v0
	v_sub_f32_e32 v6, v4, v3
	v_sub_f32_e32 v7, v4, v6
	v_sub_f32_e32 v3, v3, v7
	v_sub_f32_e32 v0, v0, v6
	v_add_f32_e32 v1, v4, v1
	v_add_f32_e32 v0, v0, v3
	v_add_f32_e32 v3, v5, v1
	v_sub_f32_e32 v4, v3, v5
	v_sub_f32_e32 v1, v1, v4
	v_add_f32_e32 v0, v0, v1
	v_mul_f32_e32 v1, 0xbfb8aa3b, v77
	v_add_f32_e32 v0, v3, v0
	v_rndne_f32_e32 v3, v1
	v_sub_f32_e32 v4, v1, v3
	v_fma_f32 v1, v77, s8, -v1
	v_fmac_f32_e32 v1, 0xb2a5705f, v77
	v_add_f32_e32 v1, v4, v1
	v_exp_f32_e32 v1, v1
	v_cvt_i32_f32_e32 v3, v3
	v_cmp_neq_f32_e32 vcc, s23, v2
	v_cmp_gt_u32_e64 s[46:47], 16, v125
	v_mov_b32_e32 v69, v16
	v_cndmask_b32_e32 v0, v236, v0, vcc
	v_cmp_lt_f32_e64 vcc, |v2|, s35
	v_mul_f32_e32 v135, 0xc1000000, v8
	v_lshl_add_u32 v8, v17, 2, 0
	v_cndmask_b32_e32 v9, v0, v2, vcc
	v_ldexp_f32 v0, v1, v3
	v_cmp_nlt_f32_e32 vcc, s9, v77
	v_lshlrev_b32_e32 v136, 3, v17
	v_or_b32_e32 v48, 16, v17
	v_cndmask_b32_e32 v0, 0, v0, vcc
	v_cmp_ngt_f32_e32 vcc, s21, v77
	v_mul_f32_e32 v137, 0xc1000000, v9
	v_or_b32_e32 v9, 32, v17
	v_cndmask_b32_e32 v2, v236, v0, vcc
	v_add_f32_e32 v3, 1.0, v2
	v_add_f32_e32 v0, -1.0, v3
	v_sub_f32_e32 v1, v0, v3
	v_add_f32_e32 v1, 1.0, v1
	v_sub_f32_e32 v0, v2, v0
	v_add_f32_e32 v4, v0, v1
	v_frexp_mant_f32_e32 v5, v3
	v_cvt_f64_f32_e32 v[0:1], v3
	v_frexp_exp_i32_f64_e32 v0, v[0:1]
	v_cmp_gt_f32_e32 vcc, s25, v5
	v_lshlrev_b32_e32 v140, 3, v9
	v_or_b32_e32 v44, 1, v73
	v_subbrev_co_u32_e32 v0, vcc, 0, v0, vcc
	v_sub_u32_e32 v1, 0, v0
	v_ldexp_f32 v3, v3, v1
	v_ldexp_f32 v1, v4, v1
	v_add_f32_e32 v4, -1.0, v3
	v_add_f32_e32 v7, 1.0, v3
	v_add_f32_e32 v5, 1.0, v4
	v_add_f32_e32 v10, -1.0, v7
	v_sub_f32_e32 v5, v3, v5
	v_sub_f32_e32 v3, v3, v10
	v_add_f32_e32 v5, v1, v5
	v_add_f32_e32 v1, v1, v3
	v_add_f32_e32 v3, v7, v1
	v_rcp_f32_e32 v10, v3
	v_add_f32_e32 v6, v4, v5
	v_sub_f32_e32 v4, v4, v6
	v_add_f32_e32 v4, v5, v4
	v_sub_f32_e32 v5, v7, v3
	v_add_f32_e32 v1, v1, v5
	v_mul_f32_e32 v5, v6, v10
	v_mul_f32_e32 v7, v3, v5
	v_fma_f32 v11, v5, v3, -v7
	v_fmac_f32_e32 v11, v5, v1
	v_add_f32_e32 v12, v7, v11
	v_sub_f32_e32 v13, v6, v12
	v_sub_f32_e32 v6, v6, v13
	v_sub_f32_e32 v7, v12, v7
	v_sub_f32_e32 v6, v6, v12
	v_add_f32_e32 v4, v4, v6
	v_sub_f32_e32 v6, v7, v11
	v_add_f32_e32 v4, v6, v4
	v_add_f32_e32 v6, v13, v4
	v_mul_f32_e32 v7, v10, v6
	v_mul_f32_e32 v11, v3, v7
	v_fma_f32 v3, v7, v3, -v11
	v_fmac_f32_e32 v3, v7, v1
	v_sub_f32_e32 v1, v13, v6
	v_add_f32_e32 v1, v4, v1
	v_add_f32_e32 v4, v11, v3
	v_sub_f32_e32 v12, v6, v4
	v_sub_f32_e32 v6, v6, v12
	v_sub_f32_e32 v11, v4, v11
	v_sub_f32_e32 v4, v6, v4
	v_add_f32_e32 v1, v1, v4
	v_sub_f32_e32 v3, v11, v3
	v_cvt_f32_i32_e32 v0, v0
	v_add_f32_e32 v1, v3, v1
	v_add_f32_e32 v3, v5, v7
	v_add_f32_e32 v1, v12, v1
	v_sub_f32_e32 v4, v3, v5
	v_mul_f32_e32 v1, v10, v1
	v_sub_f32_e32 v4, v7, v4
	v_add_f32_e32 v1, v4, v1
	v_mul_f32_e32 v7, 0x3f317218, v0
	v_add_f32_e32 v4, v3, v1
	v_fma_f32 v10, v0, s34, -v7
	v_mul_f32_e32 v5, v4, v4
	v_fmac_f32_e32 v10, 0xb102e308, v0
	v_sub_f32_e32 v0, v4, v3
	v_fmamk_f32 v6, v5, 0x3e9b6dac, v228
	v_sub_f32_e32 v0, v1, v0
	v_add_f32_e32 v1, v7, v10
	v_fmaak_f32 v6, v5, v6, 0x3f2aaada
	v_sub_f32_e32 v3, v1, v7
	v_ldexp_f32 v7, v4, 1
	v_mul_f32_e32 v4, v4, v5
	v_mul_f32_e32 v4, v4, v6
	v_add_f32_e32 v5, v7, v4
	v_sub_f32_e32 v6, v5, v7
	v_ldexp_f32 v0, v0, 1
	v_sub_f32_e32 v4, v4, v6
	v_add_f32_e32 v0, v0, v4
	v_add_f32_e32 v4, v5, v0
	v_sub_f32_e32 v5, v4, v5
	v_sub_f32_e32 v0, v0, v5
	v_add_f32_e32 v5, v1, v4
	v_sub_f32_e32 v6, v5, v1
	v_sub_f32_e32 v7, v5, v6
	v_sub_f32_e32 v3, v10, v3
	v_sub_f32_e32 v1, v1, v7
; #define LAS __attribute__((address_space(3)))
; __device__ __forceinline__ void unit(LAS unsigned char* lds, const Args& a, int l, int tk, int wave, int lane, int tid) {
;     ...
;     float ba[4], bx[4], csp[4], carry[4];
; #pragma unroll
;     for (int nt = 0; nt < 4; ++nt) { const int ch = l * LW + 64 * blk + 16 * nt + fr; ba[nt] = a.in[I_BA][ch]; bx[nt] = a.in[I_BX][ch]; csp[nt] = 8.0f * log1pf(expf(-a.in[I_LAM][ch])); carry[nt] = 0.f; }
;     const int c8 = tid & 7, chb = 64 * blk + 8 * c8;
;     LAS unsigned char* XC = lds + XC_OFF; LAS float* XCF = (LAS float*)(lds + XCF_OFF); LAS bf16* XG = (LAS bf16*)(lds + XG_OFF); LAS bf16* OUT = (LAS bf16*)(lds + OUT_OFF); LAS float* AGG = (LAS float*)(lds + AGG_OFF);
;     LAS float* CWL = (LAS float*)(lds + CWL_OFF);
;     if (tid < 320) { const int j = tid >> 6, ch = tid & 63; CWL[tid] = j < 4 ? a.in[I_CONVW][((size_t)l * 4 + j) * LW + 64 * blk + ch] : a.in[I_CONVB][l * LW + 64 * blk + ch]; }
;     __syncthreads();
;     v4u px[5], pg[2];
	v_sub_f32_e32 v4, v4, v6
	v_add_f32_e32 v1, v4, v1
	v_add_f32_e32 v4, v3, v0
	v_sub_f32_e32 v6, v4, v3
	v_sub_f32_e32 v7, v4, v6
	v_sub_f32_e32 v3, v3, v7
	v_sub_f32_e32 v0, v0, v6
	v_add_f32_e32 v1, v4, v1
	v_add_f32_e32 v0, v0, v3
	v_add_f32_e32 v3, v5, v1
	v_sub_f32_e32 v4, v3, v5
	v_sub_f32_e32 v1, v1, v4
	v_add_f32_e32 v0, v0, v1
	v_mul_f32_e32 v1, 0xbfb8aa3b, v76
	v_add_f32_e32 v0, v3, v0
	v_rndne_f32_e32 v3, v1
	v_sub_f32_e32 v4, v1, v3
	v_fma_f32 v1, v76, s8, -v1
	v_fmac_f32_e32 v1, 0xb2a5705f, v76
	v_add_f32_e32 v1, v4, v1
	v_exp_f32_e32 v1, v1
	v_cvt_i32_f32_e32 v3, v3
	v_cmp_neq_f32_e32 vcc, s23, v2
	s_movk_i32 s8, 0x1000
	v_mov_b32_e32 v62, 0
	v_cndmask_b32_e32 v0, v236, v0, vcc
	v_cmp_lt_f32_e64 vcc, |v2|, s35
	v_lshl_add_u32 v38, v38, 7, 0
	v_lshlrev_b32_e32 v40, 4, v40
	v_cndmask_b32_e32 v10, v0, v2, vcc
	v_ldexp_f32 v0, v1, v3
	v_cmp_nlt_f32_e32 vcc, s9, v76
	v_mul_f32_e32 v139, 0xc1000000, v10
	v_or_b32_e32 v10, 48, v17
	v_cndmask_b32_e32 v0, 0, v0, vcc
	v_cmp_ngt_f32_e32 vcc, s21, v76
	s_add_i32 s21, s4, 0
	s_movk_i32 s4, 0x220
	v_cndmask_b32_e32 v2, v236, v0, vcc
	v_add_f32_e32 v3, 1.0, v2
	v_add_f32_e32 v0, -1.0, v3
	v_sub_f32_e32 v1, v0, v3
	v_add_f32_e32 v1, 1.0, v1
	v_sub_f32_e32 v0, v2, v0
	v_add_f32_e32 v4, v0, v1
	v_frexp_mant_f32_e32 v5, v3
	v_cvt_f64_f32_e32 v[0:1], v3
	v_frexp_exp_i32_f64_e32 v0, v[0:1]
	v_cmp_gt_f32_e32 vcc, s25, v5
	s_add_i32 s21, s21, 0x15800
	v_lshlrev_b32_e32 v39, 4, v39
	v_subbrev_co_u32_e32 v0, vcc, 0, v0, vcc
	v_sub_u32_e32 v1, 0, v0
	v_ldexp_f32 v3, v3, v1
	v_ldexp_f32 v1, v4, v1
	v_add_f32_e32 v4, -1.0, v3
	v_add_f32_e32 v7, 1.0, v3
	v_add_f32_e32 v5, 1.0, v4
	v_add_f32_e32 v11, -1.0, v7
	v_sub_f32_e32 v5, v3, v5
	v_sub_f32_e32 v3, v3, v11
	v_add_f32_e32 v5, v1, v5
	v_add_f32_e32 v1, v1, v3
	v_add_f32_e32 v3, v7, v1
	v_rcp_f32_e32 v11, v3
	v_add_f32_e32 v6, v4, v5
	v_sub_f32_e32 v4, v4, v6
	v_add_f32_e32 v4, v5, v4
	v_sub_f32_e32 v5, v7, v3
	v_add_f32_e32 v1, v1, v5
	v_mul_f32_e32 v5, v6, v11
	v_mul_f32_e32 v7, v3, v5
	v_fma_f32 v12, v5, v3, -v7
	v_fmac_f32_e32 v12, v5, v1
	v_add_f32_e32 v13, v7, v12
	v_sub_f32_e32 v14, v6, v13
	v_sub_f32_e32 v6, v6, v14
	v_sub_f32_e32 v7, v13, v7
	v_sub_f32_e32 v6, v6, v13
	v_add_f32_e32 v4, v4, v6
	v_sub_f32_e32 v6, v7, v12
	v_add_f32_e32 v4, v6, v4
	v_add_f32_e32 v6, v14, v4
	v_mul_f32_e32 v7, v11, v6
	v_mul_f32_e32 v12, v3, v7
	v_fma_f32 v3, v7, v3, -v12
	v_fmac_f32_e32 v3, v7, v1
	v_sub_f32_e32 v1, v14, v6
	v_add_f32_e32 v1, v4, v1
	v_add_f32_e32 v4, v12, v3
	v_sub_f32_e32 v13, v6, v4
	v_sub_f32_e32 v6, v6, v13
	v_sub_f32_e32 v12, v4, v12
	v_sub_f32_e32 v4, v6, v4
	v_add_f32_e32 v1, v1, v4
	v_sub_f32_e32 v3, v12, v3
	v_cvt_f32_i32_e32 v0, v0
	v_add_f32_e32 v1, v3, v1
	v_add_f32_e32 v3, v5, v7
	v_add_f32_e32 v1, v13, v1
	v_sub_f32_e32 v4, v3, v5
	v_mul_f32_e32 v1, v11, v1
	v_sub_f32_e32 v4, v7, v4
	v_add_f32_e32 v1, v4, v1
	v_mul_f32_e32 v7, 0x3f317218, v0
	v_add_f32_e32 v4, v3, v1
	v_fma_f32 v11, v0, s34, -v7
	v_mul_f32_e32 v5, v4, v4
	v_fmac_f32_e32 v11, 0xb102e308, v0
	v_sub_f32_e32 v0, v4, v3
	v_fmamk_f32 v6, v5, 0x3e9b6dac, v228
	v_sub_f32_e32 v0, v1, v0
	v_add_f32_e32 v1, v7, v11
	v_fmaak_f32 v6, v5, v6, 0x3f2aaada
	v_sub_f32_e32 v3, v1, v7
	v_ldexp_f32 v7, v4, 1
	v_mul_f32_e32 v4, v4, v5
	v_mul_f32_e32 v4, v4, v6
	v_add_f32_e32 v5, v7, v4
	v_sub_f32_e32 v6, v5, v7
	v_ldexp_f32 v0, v0, 1
	v_sub_f32_e32 v4, v4, v6
	v_add_f32_e32 v0, v0, v4
	v_add_f32_e32 v4, v5, v0
	v_sub_f32_e32 v5, v4, v5
	v_sub_f32_e32 v0, v0, v5
	v_add_f32_e32 v5, v1, v4
	v_sub_f32_e32 v6, v5, v1
	v_sub_f32_e32 v7, v5, v6
	v_sub_f32_e32 v3, v11, v3
	v_sub_f32_e32 v1, v1, v7
	v_sub_f32_e32 v4, v4, v6
	v_add_f32_e32 v1, v4, v1
	v_add_f32_e32 v4, v3, v0
	v_sub_f32_e32 v6, v4, v3
	v_sub_f32_e32 v7, v4, v6
	v_sub_f32_e32 v3, v3, v7
	v_sub_f32_e32 v0, v0, v6
	v_add_f32_e32 v1, v4, v1
	v_add_f32_e32 v0, v0, v3
	v_add_f32_e32 v3, v5, v1
	v_sub_f32_e32 v4, v3, v5
	v_sub_f32_e32 v1, v1, v4
	v_add_f32_e32 v0, v0, v1
	v_add_f32_e32 v0, v3, v0
	v_cmp_neq_f32_e32 vcc, s23, v2
	v_xor_b32_e32 v13, v74, v125
	v_lshlrev_b32_e32 v12, 2, v75
	v_cndmask_b32_e32 v0, v236, v0, vcc
	v_cmp_lt_f32_e64 vcc, |v2|, s35
	v_readlane_b32 s23, v253, 18
	v_lshlrev_b32_e32 v13, 4, v13
	v_cndmask_b32_e32 v11, v0, v2, vcc
	v_add_co_u32_e32 v4, vcc, s8, v70
	v_readlane_b32 s8, v253, 17
	s_nop 0
	v_addc_co_u32_e32 v5, vcc, 0, v71, vcc
	global_load_dwordx4 v[0:3], v[70:71], off offset:512 nt
; #define LAS __attribute__((address_space(3)))
; __device__ __forceinline__ void unit(LAS unsigned char* lds, const Args& a, int l, int tk, int wave, int lane, int tid) {
;     ...
;             const int ti = 2 * (tid >> 3) + it;
;             float xc[8];
;             { const f32x4 c0 = *(const LAS f32x4*)(CWL + 256 + 8 * c8), c1 = *(const LAS f32x4*)(CWL + 256 + 8 * c8 + 4); xc[0] = c0[0]; xc[1] = c0[1]; xc[2] = c0[2]; xc[3] = c0[3]; xc[4] = c1[0]; xc[5] = c1[1]; xc[6] = c1[2]; xc[7] = c1[3]; }
; #pragma unroll
;             for (int j = 0; j < 4; ++j) { const v4u xr = px[it + j]; const f32x4 w0 = *(const LAS f32x4*)(CWL + 64 * j + 8 * c8), w1 = *(const LAS f32x4*)(CWL + 64 * j + 8 * c8 + 4);
;                 xc[0] += w0[0] * bf_lo(xr.x); xc[1] += w0[1] * bf_hi(xr.x); xc[2] += w0[2] * bf_lo(xr.y); xc[3] += w0[3] * bf_hi(xr.y);
;                 xc[4] += w1[0] * bf_lo(xr.z); xc[5] += w1[1] * bf_hi(xr.z); xc[6] += w1[2] * bf_lo(xr.w); xc[7] += w1[3] * bf_hi(xr.w); }
;             v4u xb; xb.x = pk2(xc[0], xc[1]); xb.y = pk2(xc[2], xc[3]); xb.z = pk2(xc[4], xc[5]); xb.w = pk2(xc[6], xc[7]);
;             *(LAS v4u*)(XC + ti * 128 + ((c8 ^ ((ti >> 1) & 7)) << 4)) = xb;
;             *(LAS f32x4*)(XCF + ti * 68 + 8 * c8) = (f32x4){xc[0], xc[1], xc[2], xc[3]}; *(LAS f32x4*)(XCF + ti * 68 + 8 * c8 + 4) = (f32x4){xc[4], xc[5], xc[6], xc[7]};
;             *(LAS v4u*)(XG + ti * 72 + 8 * c8) = pg[it];
;         }
;         if (tile + 1 < 16) LRU_FETCH(tile + 1);
;         __syncthreads();
;         f32x4 ga[4], gx[4];
;         { const int tok = 16 * wave + fr, sw = (tok >> 1) & 7;
;           const bf16x8 a0 = *(const LAS bf16x8*)(XC + tok * 128 + ((fq ^ sw) << 4)), a1 = *(const LAS bf16x8*)(XC + tok * 128 + (((4 + fq) ^ sw) << 4));
; #pragma unroll
;           for (int nt = 0; nt < 4; ++nt) { f32x4 z = (f32x4){0.f, 0.f, 0.f, 0.f};
;               const bf16x8 wa0 = __builtin_bit_cast(bf16x8, WF[(nt * 2 + 0) * 64 + lane]), wa1 = __builtin_bit_cast(bf16x8, WF[(nt * 2 + 1) * 64 + lane]);
;               const bf16x8 wx0 = __builtin_bit_cast(bf16x8, WF[(8 + nt * 2 + 0) * 64 + lane]), wx1 = __builtin_bit_cast(bf16x8, WF[(8 + nt * 2 + 1) * 64 + lane]);
;               ga[nt] = __builtin_amdgcn_mfma_f32_16x16x32_bf16(a1, wa1, __builtin_amdgcn_mfma_f32_16x16x32_bf16(a0, wa0, z, 0, 0, 0), 0, 0, 0);
	s_nop 0
	global_load_dwordx4 v[4:7], v[4:5], off offset:2048 nt
	v_cmp_lt_i32_e32 vcc, v42, v43
	v_add_u32_e32 v113, s8, v12
	s_add_i32 s8, 0, 0x1a800
	v_cndmask_b32_e32 v42, v42, v237, vcc
	v_lshlrev_b32_e32 v115, 2, v42
	v_subrev_u32_e32 v42, 32, v237
	v_cmp_lt_i32_e32 vcc, v42, v43
	v_add_u32_e32 v114, s8, v12
	v_readlane_b32 s8, v252, 7
	v_cndmask_b32_e32 v42, v42, v237, vcc
	v_lshlrev_b32_e32 v116, 2, v42
	v_mul_lo_u32 v42, v74, s4
	s_movk_i32 s4, 0x120
	v_mul_lo_u32 v43, v74, s4
	s_add_i32 s4, 0, 0x16800
	v_add_u32_e32 v119, s4, v47
	v_readlane_b32 s4, v253, 19
	v_readlane_b32 s9, v252, 8
	v_mul_f32_e32 v141, 0xc1000000, v11
	v_add_u32_e32 v120, s4, v47
	v_readlane_b32 s4, v253, 20
	v_lshl_add_u64 v[64:65], s[8:9], 0, v[68:69]
	s_movk_i32 s9, 0x110
	v_add_u32_e32 v121, s4, v47
	v_readlane_b32 s4, v253, 21
	s_movk_i32 s8, 0x90
	v_and_b32_e32 v13, 0x70, v13
	v_add_u32_e32 v122, s4, v47
	v_readlane_b32 s4, v253, 22
	v_add_u32_e32 v12, 0, v12
	v_lshlrev_b32_e32 v14, 1, v75
	v_add_u32_e32 v123, s4, v47
	v_readlane_b32 s4, v253, 23
	v_mul_lo_u32 v118, v74, s8
	v_add_u32_e32 v13, 0, v13
	v_add_u32_e32 v124, s4, v47
	v_readlane_b32 s4, v253, 24
	v_sub_u32_e32 v15, v12, v14
	v_add_u32_e32 v117, s23, v14
	v_add_u32_e32 v125, s4, v47
	v_readlane_b32 s4, v253, 25
	v_lshlrev_b32_e32 v14, 8, v74
	v_lshlrev_b32_e32 v45, 7, v44
	v_add_u32_e32 v126, s4, v47
	v_readlane_b32 s4, v253, 26
	v_mul_lo_u32 v46, v44, s9
	v_mul_lo_u32 v44, v44, s8
	v_add_u32_e32 v127, s4, v47
	v_readlane_b32 s4, v253, 27
	v_add_u32_e32 v165, s22, v74
	s_mov_b32 s3, 0
	v_add_u32_e32 v128, s4, v47
	v_readlane_b32 s4, v253, 28
	v_cmp_lt_i32_e64 s[42:43], 0, v72
	v_cmp_lt_i32_e64 s[44:45], 1, v72
	v_add_u32_e32 v129, s4, v47
	v_readlane_b32 s4, v253, 29
	v_cmp_eq_u32_e64 s[48:49], 3, v72
	v_lshlrev_b32_e32 v138, 3, v48
	v_add_u32_e32 v130, s4, v47
	s_add_i32 s4, 0, 0x18000
	v_add_u32_e32 v131, s4, v47
	v_readlane_b32 s4, v253, 30
	v_lshlrev_b32_e32 v142, 3, v10
	v_add_u32_e32 v166, 0x80, v73
	v_add_u32_e32 v132, s4, v47
	s_add_i32 s4, 0, 0x1a000
	s_cmp_eq_u32 s2, 1
	s_cselect_b64 s[50:51], -1, 0
	s_cmp_eq_u32 s2, 2
	s_cselect_b64 s[52:53], -1, 0
	s_cmp_eq_u32 s2, 3
	s_cselect_b64 s[54:55], -1, 0
	s_cmp_eq_u32 s2, 4
	s_cselect_b64 s[56:57], -1, 0
	s_cmp_eq_u32 s2, 5
	s_cselect_b64 s[58:59], -1, 0
	s_cmp_eq_u32 s2, 6
	s_cselect_b64 s[60:61], -1, 0
	s_cmp_eq_u32 s2, 7
	s_movk_i32 s2, 0x48
	v_add_u32_e32 v133, s4, v47
	v_readlane_b32 s4, v253, 31
	v_mul_lo_u32 v11, v41, s2
	v_add_u32_e32 v52, v11, v17
	v_add_u32_e32 v134, s4, v47
	v_mul_lo_u32 v47, v41, s9
	v_or_b32_e32 v41, v11, v17
	v_lshlrev_b32_e32 v41, 1, v41
	v_add_u32_e32 v143, 0, v41
	v_add_u32_e32 v144, s23, v41
	v_add_u32_e32 v41, 0x48, v11
	v_add_lshl_u32 v49, v41, v17, 1
	v_add_u32_e32 v145, 0, v49
	v_add_u32_e32 v146, s23, v49
	v_add_u32_e32 v49, 0x90, v11
	v_or_b32_e32 v50, v49, v17
	v_lshlrev_b32_e32 v50, 1, v50
	v_add_u32_e32 v147, 0, v50
	v_add_u32_e32 v148, s23, v50
	v_add_u32_e32 v50, 0xd8, v11
	v_add_lshl_u32 v51, v50, v17, 1
	v_add_u32_e32 v17, v49, v17
	v_lshl_add_u32 v154, v17, 1, 0
	v_add_u32_e32 v17, v50, v48
	v_lshl_add_u32 v156, v17, 1, s23
	v_add_u32_e32 v17, v11, v9
	v_lshl_add_u32 v157, v17, 1, s23
	v_add_u32_e32 v17, v41, v9
	v_lshl_add_u32 v158, v17, 1, s23
	v_add_u32_e32 v17, v49, v9
	v_add_u32_e32 v9, v50, v9
	v_lshl_add_u32 v160, v9, 1, s23
	v_add_u32_e32 v9, v11, v10
	v_lshl_add_u32 v161, v9, 1, s23
	v_add_u32_e32 v9, v41, v10
	v_add_u32_e32 v149, 0, v51
	v_add_u32_e32 v150, s23, v51
	v_or_b32_e32 v51, v11, v48
	v_lshl_add_u32 v162, v9, 1, s23
	v_add_u32_e32 v9, v49, v10
	v_lshl_add_u32 v152, v51, 1, s23
	v_add_u32_e32 v51, v41, v48
	v_lshl_add_u32 v163, v9, 1, s23
	v_add_u32_e32 v9, v50, v10
	s_cselect_b64 s[62:63], -1, 0
	v_lshl_add_u32 v153, v51, 1, s23
	v_add_u32_e32 v51, v49, v48
	v_lshl_add_u32 v164, v9, 1, s23
	v_add_u32_e32 v9, 0x2400, v118
	s_addk_i32 s22, 0x80
	v_lshl_add_u32 v151, v52, 1, 0
	v_lshl_add_u32 v155, v51, 1, s23
	v_lshl_add_u32 v159, v17, 1, s23
	v_add_u32_e32 v167, s22, v73
	v_add_u32_e32 v168, v13, v14
	v_add_u32_e32 v169, v12, v42
	v_add_u32_e32 v170, v15, v43
	v_add_u32_e32 v171, v13, v45
	v_add_u32_e32 v172, v12, v46
	v_add_u32_e32 v173, v15, v44
	v_add_u32_e32 v174, v38, v40
	v_add_u32_e32 v175, v38, v39
	v_add_u32_e32 v176, v117, v9
	v_add_u32_e32 v177, v8, v47
	v_mov_b32_e32 v63, v62
	v_mov_b32_e32 v70, v62
	v_mov_b32_e32 v71, v62
	s_branch .LBB0_560

; #define LAS __attribute__((address_space(3)))
; __device__ __forceinline__ unsigned pk2(float lo, float hi) { typedef __bf16 bf2_t __attribute__((ext_vector_type(2))); const f32x2 v = {lo, hi}; return __builtin_bit_cast(unsigned, __builtin_convertvector(v, bf2_t)); }
; __device__ __forceinline__ void unit(LAS unsigned char* lds, const Args& a, int l, int tk, int wave, int lane, int tid) {
;     ...
;         for (int it = 0; it < 2; ++it) {
;             const int ti = 2 * (tid >> 3) + it;
;             float xc[8];
;             { const f32x4 c0 = *(const LAS f32x4*)(CWL + 256 + 8 * c8), c1 = *(const LAS f32x4*)(CWL + 256 + 8 * c8 + 4); xc[0] = c0[0]; xc[1] = c0[1]; xc[2] = c0[2]; xc[3] = c0[3]; xc[4] = c1[0]; xc[5] = c1[1]; xc[6] = c1[2]; xc[7] = c1[3]; }
; #pragma unroll
;             for (int j = 0; j < 4; ++j) { const v4u xr = px[it + j]; const f32x4 w0 = *(const LAS f32x4*)(CWL + 64 * j + 8 * c8), w1 = *(const LAS f32x4*)(CWL + 64 * j + 8 * c8 + 4);
;                 xc[0] += w0[0] * bf_lo(xr.x); xc[1] += w0[1] * bf_hi(xr.x); xc[2] += w0[2] * bf_lo(xr.y); xc[3] += w0[3] * bf_hi(xr.y);
;                 xc[4] += w1[0] * bf_lo(xr.z); xc[5] += w1[1] * bf_hi(xr.z); xc[6] += w1[2] * bf_lo(xr.w); xc[7] += w1[3] * bf_hi(xr.w); }
;             v4u xb; xb.x = pk2(xc[0], xc[1]); xb.y = pk2(xc[2], xc[3]); xb.z = pk2(xc[4], xc[5]); xb.w = pk2(xc[6], xc[7]);
;             *(LAS v4u*)(XC + ti * 128 + ((c8 ^ ((ti >> 1) & 7)) << 4)) = xb;
;             *(LAS f32x4*)(XCF + ti * 68 + 8 * c8) = (f32x4){xc[0], xc[1], xc[2], xc[3]}; *(LAS f32x4*)(XCF + ti * 68 + 8 * c8 + 4) = (f32x4){xc[4], xc[5], xc[6], xc[7]};
;             *(LAS v4u*)(XG + ti * 72 + 8 * c8) = pg[it];
;         }
;         if (tile + 1 < 16) LRU_FETCH(tile + 1);
.LBB0_560:
	ds_read_b128 v[8:11], v113
	ds_read_b128 v[12:15], v113 offset:16
	ds_read_b128 v[38:41], v114
	ds_read_b128 v[42:45], v114 offset:16
	ds_read_b128 v[46:49], v114 offset:256
	ds_read_b128 v[50:53], v114 offset:272
	ds_read_b128 v[54:57], v114 offset:512
	ds_read_b128 v[58:61], v114 offset:528
	ds_read_b128 v[72:75], v114 offset:768
	ds_read_b128 v[76:79], v114 offset:784
	v_lshlrev_b32_e32 v80, 16, v18
	v_and_b32_e32 v81, 0xffff0000, v18
	s_waitcnt lgkmcnt(7)
	v_pk_fma_f32 v[8:9], v[38:39], v[80:81], v[8:9]
	v_lshlrev_b32_e32 v38, 16, v19
	v_and_b32_e32 v39, 0xffff0000, v19
	v_pk_fma_f32 v[10:11], v[40:41], v[38:39], v[10:11]
	v_lshlrev_b32_e32 v38, 16, v20
	v_and_b32_e32 v39, 0xffff0000, v20
	s_waitcnt lgkmcnt(6)
	v_pk_fma_f32 v[12:13], v[42:43], v[38:39], v[12:13]
	v_lshlrev_b32_e32 v38, 16, v21
	v_and_b32_e32 v39, 0xffff0000, v21
	v_lshlrev_b32_e32 v80, 16, v22
	v_and_b32_e32 v81, 0xffff0000, v22
	v_lshlrev_b32_e32 v86, 16, v23
	v_and_b32_e32 v87, 0xffff0000, v23
	v_lshlrev_b32_e32 v92, 16, v24
	v_and_b32_e32 v93, 0xffff0000, v24
	v_pk_fma_f32 v[14:15], v[44:45], v[38:39], v[14:15]
	v_lshlrev_b32_e32 v98, 16, v25
	v_and_b32_e32 v99, 0xffff0000, v25
	s_waitcnt lgkmcnt(5)
	v_pk_fma_f32 v[8:9], v[46:47], v[80:81], v[8:9]
	v_lshlrev_b32_e32 v82, 16, v26
	v_and_b32_e32 v83, 0xffff0000, v26
	v_pk_fma_f32 v[10:11], v[48:49], v[86:87], v[10:11]
	v_lshlrev_b32_e32 v88, 16, v27
	v_and_b32_e32 v89, 0xffff0000, v27
	s_waitcnt lgkmcnt(4)
	v_pk_fma_f32 v[12:13], v[50:51], v[92:93], v[12:13]
	v_lshlrev_b32_e32 v94, 16, v28
	v_and_b32_e32 v95, 0xffff0000, v28
	v_pk_fma_f32 v[14:15], v[52:53], v[98:99], v[14:15]
	v_lshlrev_b32_e32 v100, 16, v29
	v_and_b32_e32 v101, 0xffff0000, v29
	s_waitcnt lgkmcnt(3)
	v_pk_fma_f32 v[8:9], v[54:55], v[82:83], v[8:9]
	v_lshlrev_b32_e32 v84, 16, v30
	v_and_b32_e32 v85, 0xffff0000, v30
	v_pk_fma_f32 v[10:11], v[56:57], v[88:89], v[10:11]
	v_lshlrev_b32_e32 v90, 16, v31
	v_and_b32_e32 v91, 0xffff0000, v31
	s_waitcnt lgkmcnt(2)
	v_pk_fma_f32 v[12:13], v[58:59], v[94:95], v[12:13]
	v_lshlrev_b32_e32 v96, 16, v32
	v_and_b32_e32 v97, 0xffff0000, v32
	v_pk_fma_f32 v[14:15], v[60:61], v[100:101], v[14:15]
	v_lshlrev_b32_e32 v102, 16, v33
	v_and_b32_e32 v103, 0xffff0000, v33
	s_waitcnt lgkmcnt(1)
	v_pk_fma_f32 v[8:9], v[72:73], v[84:85], v[8:9]
	v_pk_fma_f32 v[10:11], v[74:75], v[90:91], v[10:11]
	s_waitcnt lgkmcnt(0)
	v_pk_fma_f32 v[12:13], v[76:77], v[96:97], v[12:13]
	v_pk_fma_f32 v[14:15], v[78:79], v[102:103], v[14:15]
	v_cvt_pk_bf16_f32 v38, v8, v9
	v_cvt_pk_bf16_f32 v39, v10, v11
	v_cvt_pk_bf16_f32 v40, v12, v13
	v_cvt_pk_bf16_f32 v41, v14, v15
	ds_write_b128 v168, v[38:41]
	ds_write_b128 v169, v[8:11] offset:16384
	ds_write_b128 v169, v[12:15] offset:16400
	s_waitcnt vmcnt(1)
	ds_write_b128 v170, v[0:3] offset:51200
	ds_read_b128 v[8:11], v113
	ds_read_b128 v[12:15], v113 offset:16
	ds_read_b128 v[38:41], v114
	ds_read_b128 v[42:45], v114 offset:16
	ds_read_b128 v[46:49], v114 offset:256
	ds_read_b128 v[50:53], v114 offset:272
	ds_read_b128 v[54:57], v114 offset:512
	ds_read_b128 v[58:61], v114 offset:528
	ds_read_b128 v[72:75], v114 offset:768
	ds_read_b128 v[76:79], v114 offset:784
	s_waitcnt lgkmcnt(7)
	v_pk_fma_f32 v[8:9], v[38:39], v[80:81], v[8:9]
	v_pk_fma_f32 v[10:11], v[40:41], v[86:87], v[10:11]
	s_waitcnt lgkmcnt(5)
	v_pk_fma_f32 v[8:9], v[46:47], v[82:83], v[8:9]
	v_lshlrev_b32_e32 v38, 16, v34
	s_waitcnt lgkmcnt(3)
	v_pk_fma_f32 v[8:9], v[54:55], v[84:85], v[8:9]
	v_and_b32_e32 v39, 0xffff0000, v34
	v_pk_fma_f32 v[10:11], v[48:49], v[88:89], v[10:11]
	v_pk_fma_f32 v[12:13], v[42:43], v[92:93], v[12:13]
	s_waitcnt lgkmcnt(1)
	v_pk_fma_f32 v[8:9], v[72:73], v[38:39], v[8:9]
	v_pk_fma_f32 v[10:11], v[56:57], v[90:91], v[10:11]
	v_lshlrev_b32_e32 v38, 16, v35
	v_and_b32_e32 v39, 0xffff0000, v35
	v_pk_fma_f32 v[12:13], v[50:51], v[94:95], v[12:13]
	v_pk_fma_f32 v[14:15], v[44:45], v[98:99], v[14:15]
	v_pk_fma_f32 v[10:11], v[74:75], v[38:39], v[10:11]
	v_pk_fma_f32 v[12:13], v[58:59], v[96:97], v[12:13]
	v_lshlrev_b32_e32 v38, 16, v36
	v_and_b32_e32 v39, 0xffff0000, v36
	v_pk_fma_f32 v[14:15], v[52:53], v[100:101], v[14:15]
	s_waitcnt lgkmcnt(0)
	v_pk_fma_f32 v[12:13], v[76:77], v[38:39], v[12:13]
	v_pk_fma_f32 v[14:15], v[60:61], v[102:103], v[14:15]
	v_lshlrev_b32_e32 v38, 16, v37
	v_and_b32_e32 v39, 0xffff0000, v37
	v_pk_fma_f32 v[14:15], v[78:79], v[38:39], v[14:15]
	v_cvt_pk_bf16_f32 v38, v8, v9
	v_cvt_pk_bf16_f32 v39, v10, v11
	v_cvt_pk_bf16_f32 v40, v12, v13
	v_cvt_pk_bf16_f32 v41, v14, v15
	s_cmpk_eq_i32 s3, 0x780
	ds_write_b128 v171, v[38:41]
	ds_write_b128 v172, v[8:11] offset:16384
	ds_write_b128 v172, v[12:15] offset:16400
	s_waitcnt vmcnt(0)
	ds_write_b128 v173, v[4:7] offset:51200
	s_cbranch_scc1 .LBB0_572
	v_add_u32_e32 v2, s3, v167
	v_mov_b64_e32 v[0:1], s[76:77]
	v_mad_i64_i32 v[0:1], s[8:9], v2, s75, v[0:1]
	v_mov_b32_e32 v69, v16
	v_add_u32_e32 v20, s3, v166
	v_lshl_add_u64 v[0:1], v[0:1], 0, v[68:69]
	v_lshl_add_u64 v[50:51], v[0:1], 0, s[36:37]
	v_cmp_lt_i32_e32 vcc, 2, v20
	v_mov_b32_e32 v8, 0
	v_mov_b32_e32 v0, 0
	v_mov_b32_e32 v1, 0
	v_mov_b32_e32 v2, 0
	v_mov_b32_e32 v3, 0
	s_and_saveexec_b64 s[8:9], vcc
	s_cbranch_execz .LBB0_563
	v_add_co_u32_e32 v0, vcc, 0xffffc000, v50
	s_nop 1
	v_addc_co_u32_e32 v1, vcc, -1, v51, vcc
	global_load_dwordx4 v[0:3], v[0:1], off offset:-512 nt
.LBB0_563:
	s_or_b64 exec, exec, s[8:9]
	v_cmp_lt_i32_e32 vcc, 1, v20
	v_mov_b32_e32 v4, 0
	v_mov_b32_e32 v5, 0
	v_mov_b32_e32 v6, 0
	v_mov_b32_e32 v7, 0
	s_and_saveexec_b64 s[8:9], vcc
	s_cbranch_execz .LBB0_565
	v_add_co_u32_e32 v4, vcc, 0xffffe000, v50
	s_nop 1
	v_addc_co_u32_e32 v5, vcc, -1, v51, vcc
	global_load_dwordx4 v[4:7], v[4:5], off offset:-3072 nt
.LBB0_565:
	s_or_b64 exec, exec, s[8:9]
	v_cmp_lt_i32_e32 vcc, 0, v20
	v_mov_b32_e32 v9, 0
	v_mov_b32_e32 v10, 0
	v_mov_b32_e32 v11, 0
	s_and_saveexec_b64 s[8:9], vcc
	s_cbranch_execz .LBB0_567
	v_add_co_u32_e32 v8, vcc, 0xfffff000, v50
	s_nop 1
	v_addc_co_u32_e32 v9, vcc, -1, v51, vcc
	global_load_dwordx4 v[8:11], v[8:9], off offset:-1536 nt
.LBB0_567:
	s_or_b64 exec, exec, s[8:9]
	v_cmp_lt_i32_e32 vcc, -1, v20
	v_mov_b32_e32 v12, 0
	v_mov_b32_e32 v13, 0
	v_mov_b32_e32 v14, 0
	v_mov_b32_e32 v15, 0
	s_and_saveexec_b64 s[8:9], vcc
	s_cbranch_execz .LBB0_569
	global_load_dwordx4 v[12:15], v[50:51], off nt
.LBB0_569:
	s_or_b64 exec, exec, s[8:9]
	v_mov_b32_e32 v18, v16
	v_mov_b32_e32 v19, v16
	v_mov_b32_e32 v17, v16
	v_cmp_lt_i32_e32 vcc, -2, v20
	s_waitcnt vmcnt(0)
	v_mov_b64_e32 v[48:49], v[30:31]
	v_mov_b64_e32 v[46:47], v[28:29]
	v_mov_b64_e32 v[44:45], v[26:27]
	v_mov_b64_e32 v[42:43], v[24:25]
	v_mov_b64_e32 v[40:41], v[22:23]
	v_mov_b64_e32 v[38:39], v[20:21]
	v_mov_b64_e32 v[36:37], v[18:19]
	v_mov_b64_e32 v[34:35], v[16:17]
	v_mov_b64_e32 v[32:33], v[14:15]
	v_mov_b64_e32 v[30:31], v[12:13]
	v_mov_b64_e32 v[28:29], v[10:11]
	v_mov_b64_e32 v[26:27], v[8:9]
	v_mov_b64_e32 v[24:25], v[6:7]
	v_mov_b64_e32 v[22:23], v[4:5]
	v_mov_b64_e32 v[20:21], v[2:3]
	v_mov_b64_e32 v[18:19], v[0:1]
	s_and_saveexec_b64 s[8:9], vcc
	s_cbranch_execz .LBB0_571
	v_add_co_u32_e32 v18, vcc, 0x1000, v50
	v_mov_b32_e32 v20, v2
	s_nop 0
	v_addc_co_u32_e32 v19, vcc, 0, v51, vcc
	global_load_dwordx4 v[34:37], v[18:19], off offset:1536 nt
	v_mov_b32_e32 v18, v0
	v_mov_b32_e32 v19, v1
	v_mov_b32_e32 v21, v3
	v_mov_b32_e32 v22, v4
	v_mov_b32_e32 v23, v5
	v_mov_b32_e32 v24, v6
	v_mov_b32_e32 v25, v7
	v_mov_b32_e32 v26, v8
	v_mov_b32_e32 v27, v9
	v_mov_b32_e32 v28, v10
	v_mov_b32_e32 v29, v11
	v_mov_b32_e32 v30, v12
	v_mov_b32_e32 v31, v13
	v_mov_b32_e32 v32, v14
	v_mov_b32_e32 v33, v15
.LBB0_571:
	s_or_b64 exec, exec, s[8:9]
	v_add_co_u32_e32 v4, vcc, 0x1000, v50
	s_nop 1
	v_addc_co_u32_e32 v5, vcc, 0, v51, vcc
	global_load_dwordx4 v[0:3], v[50:51], off offset:512 nt
	s_nop 0
	global_load_dwordx4 v[4:7], v[4:5], off offset:2048 nt

; __device__ __forceinline__ void unit(LAS unsigned char* lds, const Args& a, int l, int tk, int wave, int lane, int tid) {
;     ...
;     LRU_FETCH(0);
.LBB0_581:
	v_add_co_u32_e32 v8, vcc, 0xfffff000, v70
	v_mov_b32_e32 v12, v16
	s_nop 0
	v_addc_co_u32_e32 v9, vcc, -1, v71, vcc
	global_load_dwordx4 v[8:11], v[8:9], off offset:-1536 nt
	v_mov_b32_e32 v13, v16
	v_mov_b32_e32 v14, v16
	v_mov_b32_e32 v15, v16
	s_waitcnt vmcnt(0)
	v_mov_b64_e32 v[48:49], v[30:31]
	v_mov_b64_e32 v[46:47], v[28:29]
	v_mov_b64_e32 v[44:45], v[26:27]
	v_mov_b64_e32 v[42:43], v[24:25]
	v_mov_b64_e32 v[40:41], v[22:23]
	v_mov_b64_e32 v[38:39], v[20:21]
	v_mov_b64_e32 v[36:37], v[18:19]
	v_mov_b64_e32 v[34:35], v[16:17]
	v_mov_b64_e32 v[32:33], v[14:15]
	v_mov_b64_e32 v[30:31], v[12:13]
	v_mov_b64_e32 v[28:29], v[10:11]
	v_mov_b64_e32 v[26:27], v[8:9]
	v_mov_b64_e32 v[24:25], v[6:7]
	v_mov_b64_e32 v[22:23], v[4:5]
	v_mov_b64_e32 v[20:21], v[2:3]
	v_mov_b64_e32 v[18:19], v[0:1]
	v_mov_b64_e32 v[64:65], v[30:31]
	v_mov_b64_e32 v[44:45], v[10:11]
	v_mov_b64_e32 v[42:43], v[8:9]
	v_mov_b64_e32 v[40:41], v[6:7]
	v_mov_b64_e32 v[38:39], v[4:5]
	v_mov_b64_e32 v[36:37], v[2:3]
	v_mov_b64_e32 v[34:35], v[0:1]
	v_mov_b64_e32 v[62:63], v[28:29]
	v_mov_b64_e32 v[60:61], v[26:27]
	v_mov_b64_e32 v[58:59], v[24:25]
	v_mov_b64_e32 v[56:57], v[22:23]
	v_mov_b64_e32 v[54:55], v[20:21]
	v_mov_b64_e32 v[52:53], v[18:19]
	v_mov_b64_e32 v[50:51], v[16:17]
	v_mov_b64_e32 v[48:49], v[14:15]
	v_mov_b64_e32 v[46:47], v[12:13]
	s_or_b64 exec, exec, s[8:9]
	v_cmp_lt_i32_e32 vcc, -1, v74
	s_and_saveexec_b64 s[8:9], vcc
	s_cbranch_execnz .LBB0_555
	s_branch .LBB0_556
